# MLA rinv / rope-key phase: next row's 5 loads prefetched at row start into spare VGPRs (before the row's 18 stores), vmcnt(18) at loop end
# baseline (speedup 1.0000x reference)
.LBB0_587:
	s_or_b64 exec, exec, s[4:5]
	s_mov_b64 s[4:5], 0
	s_waitcnt lgkmcnt(0)
	v_mov_b32_e32 v0, v162
	s_barrier
	v_readlane_b32 s6, v246, 39
	v_ashrrev_i32_e32 v2, 6, v0
	s_nop 0
	v_add_u32_e32 v2, s6, v2
	s_movk_i32 s6, 0x4000
	v_cmp_gt_i32_e32 vcc, s6, v2
	s_and_saveexec_b64 s[58:59], vcc
	s_cbranch_execz .LBB0_598
	v_and_b32_e32 v0, 63, v0
	v_cvt_f32_ubyte0_e32 v3, v0
	v_mul_f32_e32 v3, 0xbd000000, v3
	v_mul_f32_e32 v5, 0x419773da, v3
	v_cmp_gt_f32_e32 vcc, s41, v5
	s_add_u32 s82, s50, s4
	s_addc_u32 s83, s51, s5
	v_cndmask_b32_e32 v5, 0, v181, vcc
	v_fmac_f32_e32 v5, 0x419773da, v3
	s_add_u32 s84, s82, 0xb900000
	v_exp_f32_e32 v3, v5
	s_addc_u32 s85, s83, 0
	s_add_u32 s86, s82, 0x40000
	s_addc_u32 s87, s83, 0
	v_cndmask_b32_e32 v5, 0, v182, vcc
	s_add_u32 s88, s82, 0x50000
	v_ldexp_f32 v5, v3, v5
	v_lshlrev_b32_e32 v3, 2, v0
	s_addc_u32 s89, s83, 0
	v_cmp_gt_u32_e64 s[8:9], 48, v0
	v_lshlrev_b32_e32 v4, 3, v0
	v_cmp_gt_u32_e64 s[4:5], 32, v0
	v_cmp_eq_u32_e64 s[6:7], 0, v0
	v_xor_b32_e32 v14, 0x80, v3
	v_xor_b32_e32 v15, 64, v3
	v_xor_b32_e32 v16, 32, v3
	v_xor_b32_e32 v17, 16, v3
	v_xor_b32_e32 v18, 8, v3
	v_xor_b32_e32 v19, 4, v3
	s_mov_b64 s[90:91], 0
	v_lshlrev_b32_e32 v6, 1, v0
	v_mov_b32_e32 v72, v2
	v_ashrrev_i32_e32 v73, 31, v2
	v_mov_b64_e32 v[70:71], s[84:85]
	v_mad_i64_i32 v[70:71], s[10:11], v72, s28, v[70:71]
	v_lshlrev_b32_e32 v52, 1, v4
	v_mov_b32_e32 v53, 0
	v_lshl_add_u64 v[54:55], v[70:71], 0, v[52:53]
	v_lshl_add_u64 v[44:45], v[72:73], 2, s[56:57]
	v_mov_b32_e32 v50, v6
	v_mov_b32_e32 v51, 0
	v_lshl_add_u64 v[48:49], v[70:71], 0, v[50:51]
	s_and_saveexec_b64 s[10:11], s[8:9]
	s_nop 1
	global_load_dwordx4 v[56:59], v[54:55], off
	s_mov_b64 exec, s[10:11]
	s_and_saveexec_b64 s[10:11], s[4:5]
	s_nop 1
	global_load_dwordx4 v[36:39], v[54:55], off offset:768
	global_load_dword v40, v[44:45], off
	global_load_ushort v41, v[48:49], off offset:1280
	global_load_ushort v42, v[48:49], off offset:1344
	s_mov_b64 exec, s[10:11]
	s_waitcnt vmcnt(0)
	s_branch .LBB0_590
.LBB0_589:
	s_or_b64 exec, exec, s[92:93]
	v_add_u32_e32 v2, s71, v2
	v_cmp_lt_i32_e32 vcc, s43, v2
	s_or_b64 s[90:91], vcc, s[90:91]
	s_andn2_b64 exec, exec, s[90:91]
	s_cbranch_execz .LBB0_598
	s_waitcnt vmcnt(18)
.LBB0_590:
	v_mov_b64_e32 v[8:9], s[84:85]
	v_mad_i64_i32 v[8:9], s[10:11], v2, s28, v[8:9]
	v_mov_b32_e32 v10, 0
	v_mov_b32_e32 v11, 0
	v_mov_b64_e32 v[20:21], v[56:57]
	v_mov_b64_e32 v[22:23], v[58:59]
	v_mov_b64_e32 v[60:61], v[36:37]
	v_mov_b64_e32 v[62:63], v[38:39]
	v_mov_b32_e32 v64, v40
	v_mov_b32_e32 v65, v41
	v_mov_b32_e32 v66, v42
	v_add_u32_e32 v72, s71, v2
	v_min_i32_e32 v72, s43, v72
	v_mov_b32_e32 v73, 0
	v_mov_b64_e32 v[70:71], s[84:85]
	v_mad_i64_i32 v[70:71], s[10:11], v72, s28, v[70:71]
	v_lshlrev_b32_e32 v52, 1, v4
	v_mov_b32_e32 v53, 0
	v_lshl_add_u64 v[54:55], v[70:71], 0, v[52:53]
	v_lshl_add_u64 v[44:45], v[72:73], 2, s[56:57]
	v_mov_b32_e32 v50, v6
	v_mov_b32_e32 v51, 0
	v_lshl_add_u64 v[48:49], v[70:71], 0, v[50:51]
	s_and_saveexec_b64 s[10:11], s[8:9]
	s_nop 1
	global_load_dwordx4 v[56:59], v[54:55], off
	s_mov_b64 exec, s[10:11]
	s_and_saveexec_b64 s[10:11], s[4:5]
	s_nop 1
	global_load_dwordx4 v[36:39], v[54:55], off offset:768
	global_load_dword v40, v[44:45], off
	global_load_ushort v41, v[48:49], off offset:1280
	global_load_ushort v42, v[48:49], off offset:1344
	s_mov_b64 exec, s[10:11]
	s_and_saveexec_b64 s[10:11], s[8:9]
	s_cbranch_execz .LBB0_592
	v_lshlrev_b32_e32 v0, 1, v4
	s_waitcnt lgkmcnt(0)
	v_lshl_add_u64 v[12:13], v[8:9], 0, v[0:1]
	v_lshlrev_b32_e32 v12, 16, v20
	v_and_b32_e32 v13, 0xffff0000, v20
	v_and_b32_e32 v20, 0xffff0000, v21
	v_lshlrev_b32_e32 v21, 16, v21
	v_pk_mul_f32 v[12:13], v[12:13], v[12:13]
	v_pk_mul_f32 v[20:21], v[20:21], v[20:21]
	v_add_f32_e32 v0, v12, v13
	v_and_b32_e32 v24, 0xffff0000, v22
	v_lshlrev_b32_e32 v25, 16, v22
	v_add_f32_e32 v0, v21, v0
	v_pk_mul_f32 v[24:25], v[24:25], v[24:25]
	v_add_f32_e32 v0, v20, v0
	v_and_b32_e32 v22, 0xffff0000, v23
	v_lshlrev_b32_e32 v23, 16, v23
	v_add_f32_e32 v0, v25, v0
	v_pk_mul_f32 v[22:23], v[22:23], v[22:23]
	v_add_f32_e32 v0, v24, v0
	v_add_f32_e32 v0, v23, v0
	v_add_f32_e32 v11, v22, v0
.LBB0_592:
	s_or_b64 exec, exec, s[10:11]
	s_and_saveexec_b64 s[10:11], s[4:5]
	s_cbranch_execz .LBB0_594
	v_lshlrev_b32_e32 v0, 1, v4
	s_waitcnt lgkmcnt(0)
	v_lshl_add_u64 v[12:13], v[8:9], 0, v[0:1]
	v_mov_b64_e32 v[20:21], v[60:61]
	v_mov_b64_e32 v[22:23], v[62:63]
	v_lshlrev_b32_e32 v12, 16, v20
	v_and_b32_e32 v13, 0xffff0000, v20
	v_and_b32_e32 v20, 0xffff0000, v21
	v_lshlrev_b32_e32 v21, 16, v21
	v_pk_mul_f32 v[12:13], v[12:13], v[12:13]
	v_pk_mul_f32 v[20:21], v[20:21], v[20:21]
	v_add_f32_e32 v0, v12, v13
	v_and_b32_e32 v24, 0xffff0000, v22
	v_lshlrev_b32_e32 v25, 16, v22
	v_add_f32_e32 v0, v21, v0
	v_pk_mul_f32 v[24:25], v[24:25], v[24:25]
	v_add_f32_e32 v0, v20, v0
	v_and_b32_e32 v22, 0xffff0000, v23
	v_lshlrev_b32_e32 v23, 16, v23
	v_add_f32_e32 v0, v25, v0
	v_pk_mul_f32 v[22:23], v[22:23], v[22:23]
	v_add_f32_e32 v0, v24, v0
	v_add_f32_e32 v0, v23, v0
	v_add_f32_e32 v10, v22, v0

.LBB0_596:
	s_or_b64 exec, exec, s[60:61]
	s_and_saveexec_b64 s[92:93], s[4:5]
	s_cbranch_execz .LBB0_589
	v_lshl_add_u64 v[10:11], v[2:3], 2, s[56:57]
	v_mov_b32_e32 v0, v64
	v_mov_b32_e32 v7, v1
	v_lshl_add_u64 v[8:9], v[8:9], 0, v[6:7]
	v_mov_b32_e32 v3, v65
	v_mov_b32_e32 v32, v66
	v_mov_b64_e32 v[8:9], s[82:83]
	v_mad_i64_i32 v[8:9], s[10:11], v2, s0, v[8:9]
	v_lshl_add_u64 v[8:9], v[8:9], 0, v[6:7]
	s_mov_b64 s[10:11], 0x10100100
	v_lshl_add_u64 v[10:11], v[8:9], 0, s[10:11]
	s_mov_b32 s10, 0x10d00000
	s_waitcnt lgkmcnt(0)
	v_add_co_u32_e32 v12, vcc, s10, v8
	s_mov_b32 s10, 0x10100000
	v_add_co_u32_e64 v20, s[10:11], s10, v8
	s_mov_b32 s40, 0x11300000
	s_nop 0
	v_addc_co_u32_e64 v21, s[10:11], 0, v9, s[10:11]
	s_mov_b32 s10, 0x10700000
	s_nop 0
	v_add_co_u32_e64 v22, s[10:11], s10, v8
	v_cvt_f32_i32_e32 v0, v0
	v_addc_co_u32_e64 v23, s[10:11], 0, v9, s[10:11]
	s_mov_b64 s[10:11], vcc
	v_mul_f32_e32 v0, v5, v0
	v_mul_f32_e32 v7, 0.15915494, v0
	v_rndne_f32_e32 v7, v7
	v_fmac_f32_e32 v0, 0xc0c90000, v7
	v_fmac_f32_e32 v0, 0xbafdaa22, v7
	v_add_co_u32_e32 v24, vcc, s40, v8
	v_addc_co_u32_e64 v13, s[10:11], 0, v9, s[10:11]
	v_mul_f32_e32 v0, 0.15915494, v0
	s_mov_b64 s[10:11], vcc
	s_mov_b32 s40, 0x11900000
	v_sin_f32_e32 v7, v0
	v_add_co_u32_e32 v26, vcc, s40, v8
	v_addc_co_u32_e64 v25, s[10:11], 0, v9, s[10:11]
	v_cos_f32_e32 v0, v0
	s_mov_b64 s[10:11], vcc
	v_add_co_u32_e32 v28, vcc, 0x11f00000, v8
	v_addc_co_u32_e64 v27, s[10:11], 0, v9, s[10:11]
	v_lshlrev_b32_e32 v32, 16, v32
	s_mov_b64 s[10:11], vcc
	v_lshlrev_b32_e32 v3, 16, v3
	v_mul_f32_e32 v33, v7, v32
	v_add_co_u32_e32 v30, vcc, 0x12500000, v8
	v_addc_co_u32_e64 v29, s[10:11], 0, v9, s[10:11]
	v_mul_f32_e32 v7, v7, v3
	v_fma_f32 v3, v0, v3, -v33
	s_mov_b64 s[10:11], vcc
	v_add_co_u32_e32 v8, vcc, 0x12b00000, v8
	v_fmac_f32_e32 v7, v0, v32
	v_cvt_pk_bf16_f32 v0, v3, s0
	v_addc_co_u32_e64 v31, s[10:11], 0, v9, s[10:11]
	v_addc_co_u32_e32 v9, vcc, 0, v9, vcc
	v_cvt_pk_bf16_f32 v3, v7, s0
	global_store_short v[20:21], v0, off offset:256
	global_store_short v[10:11], v3, off offset:64
	global_store_short v[22:23], v0, off offset:256
	global_store_short v[22:23], v3, off offset:320
	global_store_short v[12:13], v0, off offset:256
	global_store_short v[12:13], v3, off offset:320
	global_store_short v[24:25], v0, off offset:256
	global_store_short v[24:25], v3, off offset:320
	global_store_short v[26:27], v0, off offset:256
	global_store_short v[26:27], v3, off offset:320
	global_store_short v[28:29], v0, off offset:256
	global_store_short v[28:29], v3, off offset:320
	global_store_short v[30:31], v0, off offset:256
	global_store_short v[30:31], v3, off offset:320
	global_store_short v[8:9], v0, off offset:256
	global_store_short v[8:9], v3, off offset:320
	s_branch .LBB0_589
